# MoBA block selection loop: kmean LDS reads issued 8 deep into idle chunk-staging registers (was 1 ahead: each 4-fma group waited an LDS round trip)
# speedup vs baseline: 1.0086x; 1.0019x over previous
; #define LAS __attribute__((address_space(3)))
; __device__ __forceinline__ void phase_moba_attn(const Params& P, LAS unsigned char* lds, int l, int qslot) {
;     ...
;             for (int j = 0; j < i; ++j) {
;                 const LAS float* kr = km + j * HD + 8 * hf;
;                 float a = 0.f;
; #pragma unroll
;                 for (int st = 0; st < 8; ++st) { const f32x4 k0 = *(const LAS f32x4*)(kr + 16 * st), k1 = *(const LAS f32x4*)(kr + 16 * st + 4);
;                     a = fmaf((float)qf[st][0], k0[0], a); a = fmaf((float)qf[st][1], k0[1], a); a = fmaf((float)qf[st][2], k0[2], a); a = fmaf((float)qf[st][3], k0[3], a);
;                     a = fmaf((float)qf[st][4], k1[0], a); a = fmaf((float)qf[st][5], k1[1], a); a = fmaf((float)qf[st][6], k1[2], a); a = fmaf((float)qf[st][7], k1[3], a); }
;                 const float b2 = __shfl_xor(a, 32);
;                 const float x2 = (hf == 0) ? (a + b2) : (b2 + a);
;                 if (x2 > v0) { v2 = v1; i2 = i1; v1 = v0; i1 = i0; v0 = x2; i0 = j; }
;                 else if (x2 > v1) { v2 = v1; i2 = i1; v1 = x2; i1 = j; }
;                 else if (x2 > v2) { v2 = x2; i2 = j; }
.LBB0_896:
	v_add_u32_e32 v82, s1, v242
	v_add_u32_e32 v74, 0x11000, v82
	ds_read_b128 v[130:133], v74
	ds_read_b128 v[134:137], v74 offset:16
	ds_read_b128 v[138:141], v74 offset:64
	ds_read_b128 v[142:145], v74 offset:80
	ds_read_b128 v[146:149], v74 offset:128
	ds_read_b128 v[150:153], v74 offset:144
	ds_read_b128 v[154:157], v74 offset:192
	ds_read_b128 v[158:161], v74 offset:208
	s_waitcnt lgkmcnt(7)
	v_fma_f32 v83, v4, v130, 0
	v_fmac_f32_e32 v83, v5, v131
	v_fmac_f32_e32 v83, v6, v132
	v_fmac_f32_e32 v83, v7, v133
	ds_read_b128 v[130:133], v74 offset:256
	s_waitcnt lgkmcnt(7)
	v_fmac_f32_e32 v83, v8, v134
	v_fmac_f32_e32 v83, v9, v135
	v_fmac_f32_e32 v83, v10, v136
	v_fmac_f32_e32 v83, v11, v137
	ds_read_b128 v[134:137], v74 offset:272
	s_waitcnt lgkmcnt(7)
	v_fmac_f32_e32 v83, v12, v138
	v_fmac_f32_e32 v83, v13, v139
	v_fmac_f32_e32 v83, v14, v140
	v_fmac_f32_e32 v83, v15, v141
	ds_read_b128 v[138:141], v74 offset:320
	s_waitcnt lgkmcnt(7)
	v_fmac_f32_e32 v83, v16, v142
	v_fmac_f32_e32 v83, v17, v143
	v_fmac_f32_e32 v83, v18, v144
	v_fmac_f32_e32 v83, v19, v145
	ds_read_b128 v[142:145], v74 offset:336
	s_waitcnt lgkmcnt(7)
	v_fmac_f32_e32 v83, v20, v146
	v_fmac_f32_e32 v83, v21, v147
	v_fmac_f32_e32 v83, v22, v148
	v_fmac_f32_e32 v83, v23, v149
	ds_read_b128 v[146:149], v74 offset:384
	s_waitcnt lgkmcnt(7)
	v_fmac_f32_e32 v83, v24, v150
	v_fmac_f32_e32 v83, v25, v151
	v_fmac_f32_e32 v83, v26, v152
	v_fmac_f32_e32 v83, v27, v153
	ds_read_b128 v[150:153], v74 offset:400
	s_waitcnt lgkmcnt(7)
	v_fmac_f32_e32 v83, v28, v154
	v_fmac_f32_e32 v83, v29, v155
	v_fmac_f32_e32 v83, v30, v156
	v_fmac_f32_e32 v83, v31, v157
	ds_read_b128 v[154:157], v74 offset:448
	s_waitcnt lgkmcnt(7)
	v_fmac_f32_e32 v83, v32, v158
	v_fmac_f32_e32 v83, v33, v159
	v_fmac_f32_e32 v83, v34, v160
	v_fmac_f32_e32 v83, v35, v161
	ds_read_b128 v[158:161], v74 offset:464
	s_waitcnt lgkmcnt(7)
	v_fmac_f32_e32 v83, v36, v130
	v_fmac_f32_e32 v83, v37, v131
	v_fmac_f32_e32 v83, v38, v132
	v_fmac_f32_e32 v83, v39, v133
	s_waitcnt lgkmcnt(6)
	v_fmac_f32_e32 v83, v40, v134
	v_fmac_f32_e32 v83, v41, v135
	v_fmac_f32_e32 v83, v42, v136
	v_fmac_f32_e32 v83, v43, v137
	s_waitcnt lgkmcnt(5)
	v_fmac_f32_e32 v83, v44, v138
	v_fmac_f32_e32 v83, v45, v139
	v_fmac_f32_e32 v83, v46, v140
	v_fmac_f32_e32 v83, v47, v141
	s_waitcnt lgkmcnt(4)
	v_fmac_f32_e32 v83, v48, v142
	v_fmac_f32_e32 v83, v49, v143
	v_fmac_f32_e32 v83, v50, v144
	v_fmac_f32_e32 v83, v51, v145
	s_waitcnt lgkmcnt(3)
	v_fmac_f32_e32 v83, v52, v146
	v_fmac_f32_e32 v83, v53, v147
	v_fmac_f32_e32 v83, v54, v148
	v_fmac_f32_e32 v83, v55, v149
	s_waitcnt lgkmcnt(2)
	v_fmac_f32_e32 v83, v56, v150
	v_fmac_f32_e32 v83, v57, v151
	v_fmac_f32_e32 v83, v58, v152
	v_fmac_f32_e32 v83, v59, v153
	s_waitcnt lgkmcnt(1)
	v_fmac_f32_e32 v83, v60, v154
	v_fmac_f32_e32 v83, v61, v155
	v_fmac_f32_e32 v83, v62, v156
	v_fmac_f32_e32 v83, v63, v157
	s_waitcnt lgkmcnt(0)
	v_fmac_f32_e32 v83, v64, v158
	v_fmac_f32_e32 v83, v65, v159
	v_fmac_f32_e32 v83, v66, v160
	v_fmac_f32_e32 v83, v67, v161
	ds_bpermute_b32 v74, v2, v83
	v_mov_b32_e32 v76, s18
	v_mov_b32_e32 v75, v71
	v_mov_b32_e32 v77, v69
	s_waitcnt lgkmcnt(0)
	v_add_f32_e32 v74, v83, v74
	v_cmp_ngt_f32_e32 vcc, v74, v69
	s_and_saveexec_b64 s[12:13], vcc
	s_cbranch_execz .LBB0_902
	v_cmp_ngt_f32_e32 vcc, v74, v70
	v_mov_b32_e32 v75, s18
	s_and_saveexec_b64 s[20:21], vcc
	s_cbranch_execz .LBB0_901
	v_cmp_gt_f32_e32 vcc, v74, v73
	s_and_saveexec_b64 s[26:27], vcc
	v_mov_b32_e32 v72, s18
	v_mov_b32_e32 v73, v74
	s_or_b64 exec, exec, s[26:27]
	v_mov_b32_e32 v74, v70
	v_mov_b32_e32 v70, v73
	v_mov_b32_e32 v75, v68
	v_mov_b32_e32 v68, v72
